# attn64 K tile: LDS swizzle keyed on (row>>1)&7 so the 16-lane groups of ds_read_b128 hit distinct banks
# speedup vs baseline: 1.0080x; 1.0023x over previous
.LBB0_926:
	v_mov_b32_e32 v69, v0
	s_lshl_b64 s[10:11], s[18:19], 1
	s_add_u32 s12, s42, s10
	v_bfe_u32 v68, v69, 5, 1
	v_and_b32_e32 v3, 31, v69
	v_lshlrev_b32_e32 v36, 4, v68
	s_addc_u32 s13, s43, s11
	v_lshl_or_b32 v4, v3, 12, v36
	global_load_dwordx4 v[176:179], v4, s[12:13]
	global_load_dwordx4 v[172:175], v4, s[12:13] offset:32
	global_load_dwordx4 v[168:171], v4, s[12:13] offset:64
	global_load_dwordx4 v[164:167], v4, s[12:13] offset:96
	s_add_u32 s66, s44, s10
	s_addc_u32 s67, s45, s11
	v_ashrrev_i32_e32 v4, 6, v69
	s_add_i32 s77, 0, 0x1c800
	v_lshrrev_b32_e32 v6, 4, v69
	v_bfe_u32 v7, v69, 2, 3
	s_mov_b32 s6, 0x1ffff8
	v_mov_b32_e32 v5, s77
	v_and_or_b32 v6, v6, s6, v7
	v_readfirstlane_b32 s6, v4
	ds_read_b32 v192, v5
	v_lshlrev_b32_e32 v5, 1, v4
	s_lshl_b32 s6, s6, 10
	v_and_or_b32 v5, v5, 2, v68
	v_lshlrev_b32_e32 v7, 4, v69
	s_cmp_lg_u32 0, -1
	v_lshlrev_b32_e32 v6, 11, v6
	v_lshlrev_b32_e32 v5, 6, v5
	v_and_b32_e32 v7, 48, v7
	s_cselect_b32 s10, 0, 0
	v_or3_b32 v194, v5, v7, v6
	v_bfe_u32 v5, v69, 3, 3
	s_add_i32 s14, s6, s10
	s_add_i32 s10, 0, 0x14000
	s_waitcnt vmcnt(0) lgkmcnt(0)
	s_barrier
	v_bfe_u32 v6, v69, 4, 3
	v_bitop3_b32 v6, v6, v69, 7 bitop3:0x78
	s_cmp_lg_u32 s10, -1
	s_mov_b32 s12, m0
	s_mov_b32 m0, s14
	s_nop 0
	global_load_lds_dwordx4 v194, s[52:53]
	s_mov_b32 m0, s12
	v_lshlrev_b32_e32 v6, 4, v6
	v_lshlrev_b32_e32 v7, 14, v4
	v_lshlrev_b32_e32 v5, 11, v5
	s_cselect_b32 s11, s10, 0
	s_add_i32 s12, s14, 0x2000
	s_mov_b32 s13, m0
	s_mov_b32 m0, s12
	s_nop 0
	global_load_lds_dwordx4 v194, s[54:55]
	s_mov_b32 m0, s13
	v_or3_b32 v195, v5, v7, v6
	s_add_i32 s11, s6, s11
	s_mov_b32 s12, m0
	s_mov_b32 m0, s11
	s_nop 0
	global_load_lds_dwordx4 v195, s[66:67]
	s_mov_b32 m0, s12
	s_add_u32 s12, s66, 0x20000
	s_addc_u32 s13, s67, 0
	s_add_i32 s15, s14, 0x4000
	s_mov_b32 s18, m0
	s_mov_b32 m0, s15
	s_nop 0
	global_load_lds_dwordx4 v194, s[56:57]
	s_mov_b32 m0, s18
	s_addk_i32 s14, 0x6000
	s_mov_b32 s15, m0
	s_mov_b32 m0, s14
	s_nop 0
	global_load_lds_dwordx4 v194, s[58:59]
	s_mov_b32 m0, s15
	s_add_i32 s17, s11, 0x2000
	s_mov_b32 s14, m0
	s_mov_b32 m0, s17
	s_nop 0
	global_load_lds_dwordx4 v195, s[12:13]
	s_mov_b32 m0, s14
	v_readfirstlane_b32 s35, v186
	v_readfirstlane_b32 s82, v187
	v_cmp_lt_i32_e32 vcc, 3, v4
	s_and_saveexec_b64 s[18:19], vcc
	s_setprio 1
	s_or_b64 exec, exec, s[18:19]
	s_add_u32 s12, s66, 0x40000
	s_addc_u32 s13, s67, 0
	s_cmp_lg_u32 0, -1
	s_cselect_b32 s14, 0, 0
	s_add_i32 s14, s14, s6
	s_add_i32 s15, s14, 0x8000
	s_cmp_lg_u32 s10, -1
	v_mov_b32_e32 v82, 0
	s_cselect_b32 s17, s10, 0
	s_add_i32 s17, s17, s6
	v_mov_b32_e32 v83, v82
	v_mov_b32_e32 v84, v82
	v_mov_b32_e32 v85, v82
	v_mov_b32_e32 v86, v82
	v_mov_b32_e32 v87, v82
	v_mov_b32_e32 v88, v82
	v_mov_b32_e32 v89, v82
	v_mov_b32_e32 v90, v82
	v_mov_b32_e32 v91, v82
	v_mov_b32_e32 v92, v82
	v_mov_b32_e32 v93, v82
	v_mov_b32_e32 v94, v82
	v_mov_b32_e32 v95, v82
	v_mov_b32_e32 v96, v82
	v_mov_b32_e32 v97, v82
	s_waitcnt vmcnt(0)
	s_barrier
	s_addk_i32 s17, 0x4000
	s_add_i32 s14, s14, 0xa000
	s_mov_b32 s18, m0
	s_mov_b32 m0, s15
	s_nop 0
	global_load_lds_dwordx4 v194, s[60:61]
	s_mov_b32 m0, s18
	s_cmpk_gt_i32 s82, 0xff41
	s_mov_b32 s15, m0
	s_mov_b32 m0, s14
	s_nop 0
	global_load_lds_dwordx4 v194, s[62:63]
	s_mov_b32 m0, s15
	s_cselect_b64 s[68:69], -1, 0
	s_cmpk_lt_i32 s82, 0xff42
	s_mov_b32 s14, m0
	s_mov_b32 m0, s17
	s_nop 0
	global_load_lds_dwordx4 v195, s[12:13]
	s_mov_b32 m0, s14
	s_cselect_b64 vcc, -1, 0
	s_waitcnt lgkmcnt(0)
	v_cndmask_b32_e32 v98, 0, v192, vcc
	v_cmp_neq_f32_e32 vcc, 0, v98
	s_cbranch_vccz .LBB0_930
	v_mov_b32_e32 v99, v98
	v_mov_b32_e32 v100, v98
	v_mov_b32_e32 v101, v98
	v_mov_b32_e32 v102, v98
	v_mov_b32_e32 v103, v98
	v_mov_b32_e32 v104, v98
	v_mov_b32_e32 v105, v98
	v_mov_b32_e32 v106, v98
	v_mov_b32_e32 v107, v98
	v_mov_b32_e32 v108, v98
	v_mov_b32_e32 v109, v98
	v_mov_b32_e32 v110, v98
	v_mov_b32_e32 v111, v98
	v_mov_b32_e32 v112, v98
	v_mov_b32_e32 v113, v98
	v_mov_b64_e32 v[82:83], v[98:99]
	v_mov_b64_e32 v[84:85], v[100:101]
	v_mov_b64_e32 v[86:87], v[102:103]
	v_mov_b64_e32 v[88:89], v[104:105]
	v_mov_b64_e32 v[90:91], v[106:107]
	v_mov_b64_e32 v[92:93], v[108:109]
	v_mov_b64_e32 v[94:95], v[110:111]
	v_mov_b64_e32 v[96:97], v[112:113]
	s_branch .LBB0_931

.LBB0_931:
	v_lshlrev_b32_e32 v99, 7, v3
	v_lshlrev_b32_e32 v4, 3, v3
	v_add_u32_e32 v46, s10, v99
	s_movk_i32 s10, 0x70
	v_bitop3_b32 v202, v36, v4, s10 bitop3:0x78
	v_and_b32_e32 v37, 0x70, v4
	v_add_u32_e32 v4, v46, v202
	ds_read_b128 v[20:23], v4
	ds_read_b128 v[38:41], v4 offset:4096
	s_waitcnt vmcnt(0) lgkmcnt(0)
	v_mfma_f32_32x32x16_bf16 v[4:19], v[20:23], v[176:179], v[82:97]
	v_bitop3_b32 v203, v36, v37, 32 bitop3:0x36
	v_add_u32_e32 v42, v46, v203
	v_bitop3_b32 v197, v36, v37, 64 bitop3:0x36
	s_movk_i32 s10, 0x60
	v_bitop3_b32 v196, v36, v37, s10 bitop3:0x36
	s_cmp_gt_i32 s35, -1
	s_cselect_b64 s[12:13], -1, 0
	s_waitcnt lgkmcnt(0)
	v_mfma_f32_32x32x16_bf16 v[20:35], v[38:41], v[176:179], v[82:97]
	ds_read_b128 v[38:41], v42
	ds_read_b128 v[42:45], v42 offset:4096
	s_mov_b64 s[18:19], -1
	s_waitcnt vmcnt(2) lgkmcnt(1)
	v_mfma_f32_32x32x16_bf16 v[4:19], v[38:41], v[172:175], v[4:19]
	s_waitcnt lgkmcnt(0)
	v_mfma_f32_32x32x16_bf16 v[20:35], v[42:45], v[172:175], v[20:35]
	v_add_u32_e32 v42, v46, v197
	ds_read_b128 v[38:41], v42
	ds_read_b128 v[42:45], v42 offset:4096
	s_waitcnt vmcnt(1) lgkmcnt(1)
	v_mfma_f32_32x32x16_bf16 v[4:19], v[38:41], v[168:171], v[4:19]
	v_add_u32_e32 v40, v46, v196
	s_waitcnt lgkmcnt(0)
	v_mfma_f32_32x32x16_bf16 v[20:35], v[42:45], v[168:171], v[20:35]
	ds_read_b128 v[36:39], v40
	ds_read_b128 v[40:43], v40 offset:4096
	s_waitcnt vmcnt(0) lgkmcnt(1)
	v_mfma_f32_32x32x16_bf16 v[4:19], v[36:39], v[164:167], v[4:19]
	v_cndmask_b32_e64 v36, 0, 1, s[12:13]
	s_nop 0
	v_readfirstlane_b32 s10, v36
	s_bitcmp1_b32 s10, 0
	s_cselect_b64 s[12:13], -1, 0
	s_and_b64 vcc, exec, s[12:13]
	s_waitcnt lgkmcnt(0)
	v_mfma_f32_32x32x16_bf16 v[20:35], v[40:43], v[164:167], v[20:35]
	s_cbranch_vccz .LBB0_973
	s_andn2_b64 vcc, exec, s[18:19]
	s_cbranch_vccnz .LBB0_936
